# v41 with MFMA order inside each 8-group changed so the first operand stays constant for 4 consecutive MFMAs
# baseline (speedup 1.0000x reference)
.LBB0_159:
	s_add_u32 s0, s22, 0xfff80080
	s_addc_u32 s1, s23, -1
	s_add_i32 s51, 0, 0x10000
	s_cmp_eq_u32 s50, 28
	s_cselect_b32 s27, s15, s1
	s_cselect_b32 s26, s46, s0
	v_add_u32_e32 v140, s51, v143
	s_cselect_b32 s25, s13, s49
	s_cselect_b32 s24, s47, s48
	s_add_i32 s0, 0, 0x14000
	ds_read_b128 v[146:149], v140
	ds_read_b128 v[150:153], v140 offset:1024
	ds_read_b128 v[154:157], v140 offset:2048
	ds_read_b128 v[158:161], v140 offset:3072
	v_add_u32_e32 v140, s0, v143
	ds_read_b128 v[162:165], v140
	ds_read_b128 v[166:169], v140 offset:1024
	ds_read_b128 v[170:173], v140 offset:2048
	ds_read_b128 v[174:177], v140 offset:3072
	v_lshl_add_u64 v[140:141], s[22:23], 0, v[136:137]
	s_add_i32 m0, s35, 0xc000
	ds_read_b128 v[178:181], v144
	ds_read_b128 v[182:185], v144 offset:1024
	ds_read_b128 v[192:195], v144 offset:2048
	ds_read_b128 v[196:199], v144 offset:3072
	ds_read_b128 v[200:203], v144 offset:4096
	ds_read_b128 v[204:207], v144 offset:5120
	ds_read_b128 v[208:211], v144 offset:6144
	ds_read_b128 v[212:215], v144 offset:7168
	global_load_lds_dwordx4 v[140:141], off
	v_lshl_add_u64 v[140:141], s[22:23], 0, v[138:139]
	s_add_i32 m0, s35, 0xe000
	s_nop 0
	global_load_lds_dwordx4 v[140:141], off
	s_waitcnt vmcnt(8)
	s_waitcnt lgkmcnt(0)
	s_setprio 1
	s_barrier

	v_mfma_f32_16x16x32_bf16 v[126:129], v[146:149], v[178:181], v[126:129]
	v_mfma_f32_16x16x32_bf16 v[110:113], v[146:149], v[192:195], v[110:113]
	v_mfma_f32_16x16x32_bf16 v[94:97], v[146:149], v[200:203], v[94:97]
	v_mfma_f32_16x16x32_bf16 v[78:81], v[146:149], v[208:211], v[78:81]
	v_mfma_f32_16x16x32_bf16 v[118:121], v[154:157], v[178:181], v[118:121]
	v_mfma_f32_16x16x32_bf16 v[102:105], v[154:157], v[192:195], v[102:105]
	v_mfma_f32_16x16x32_bf16 v[86:89], v[154:157], v[200:203], v[86:89]
	v_mfma_f32_16x16x32_bf16 v[70:73], v[154:157], v[208:211], v[70:73]
	v_mfma_f32_16x16x32_bf16 v[126:129], v[150:153], v[182:185], v[126:129]
	v_mfma_f32_16x16x32_bf16 v[110:113], v[150:153], v[196:199], v[110:113]
	v_mfma_f32_16x16x32_bf16 v[94:97], v[150:153], v[204:207], v[94:97]
	v_mfma_f32_16x16x32_bf16 v[78:81], v[150:153], v[212:215], v[78:81]
	v_mfma_f32_16x16x32_bf16 v[118:121], v[158:161], v[182:185], v[118:121]
	v_mfma_f32_16x16x32_bf16 v[102:105], v[158:161], v[196:199], v[102:105]
	v_mfma_f32_16x16x32_bf16 v[86:89], v[158:161], v[204:207], v[86:89]
	v_mfma_f32_16x16x32_bf16 v[70:73], v[158:161], v[212:215], v[70:73]


	v_mfma_f32_16x16x32_bf16 v[122:125], v[162:165], v[178:181], v[122:125]
	v_mfma_f32_16x16x32_bf16 v[106:109], v[162:165], v[192:195], v[106:109]
	v_mfma_f32_16x16x32_bf16 v[90:93], v[162:165], v[200:203], v[90:93]
	v_mfma_f32_16x16x32_bf16 v[74:77], v[162:165], v[208:211], v[74:77]
	v_mfma_f32_16x16x32_bf16 v[114:117], v[170:173], v[178:181], v[114:117]
	v_mfma_f32_16x16x32_bf16 v[98:101], v[170:173], v[192:195], v[98:101]
	v_mfma_f32_16x16x32_bf16 v[82:85], v[170:173], v[200:203], v[82:85]
	v_mfma_f32_16x16x32_bf16 v[66:69], v[170:173], v[208:211], v[66:69]
	v_mfma_f32_16x16x32_bf16 v[122:125], v[166:169], v[182:185], v[122:125]
	v_mfma_f32_16x16x32_bf16 v[106:109], v[166:169], v[196:199], v[106:109]
	v_mfma_f32_16x16x32_bf16 v[90:93], v[166:169], v[204:207], v[90:93]
	v_mfma_f32_16x16x32_bf16 v[74:77], v[166:169], v[212:215], v[74:77]
	v_mfma_f32_16x16x32_bf16 v[114:117], v[174:177], v[182:185], v[114:117]
	v_mfma_f32_16x16x32_bf16 v[98:101], v[174:177], v[196:199], v[98:101]
	v_mfma_f32_16x16x32_bf16 v[82:85], v[174:177], v[204:207], v[82:85]
	v_mfma_f32_16x16x32_bf16 v[66:69], v[174:177], v[212:215], v[66:69]
	s_barrier
	s_setprio 0
	s_add_i32 s1, s51, s31
	v_lshl_add_u64 v[140:141], s[24:25], 0, v[186:187]
	s_mov_b32 m0, s1
	ds_read_b128 v[178:181], v144 offset:16384
	ds_read_b128 v[182:185], v144 offset:17408
	ds_read_b128 v[192:195], v144 offset:18432
	ds_read_b128 v[196:199], v144 offset:19456
	ds_read_b128 v[200:203], v144 offset:20480
	ds_read_b128 v[204:207], v144 offset:21504
	ds_read_b128 v[208:211], v144 offset:22528
	ds_read_b128 v[212:215], v144 offset:23552
	global_load_lds_dwordx4 v[140:141], off
	s_add_i32 m0, s1, 0x2000
	s_add_u32 s52, s24, 0x80000
	v_lshl_add_u64 v[216:217], s[24:25], 0, v[130:131]
	s_addc_u32 s53, s25, 0
	s_add_i32 s0, s0, s31
	global_load_lds_dwordx4 v[216:217], off
	v_lshl_add_u64 v[218:219], s[52:53], 0, v[186:187]
	s_mov_b32 m0, s0
	v_lshl_add_u64 v[220:221], s[26:27], 0, v[132:133]
	global_load_lds_dwordx4 v[218:219], off
	v_lshl_add_u64 v[218:219], s[52:53], 0, v[130:131]
	s_add_i32 m0, s0, 0x2000
	s_nop 0
	global_load_lds_dwordx4 v[218:219], off
	v_lshl_add_u64 v[218:219], s[26:27], 0, v[134:135]
	s_mov_b32 m0, s35
	s_nop 0
	global_load_lds_dwordx4 v[218:219], off
	s_mov_b32 m0, s36
	s_nop 0
	global_load_lds_dwordx4 v[220:221], off
	s_waitcnt vmcnt(8)
	s_waitcnt lgkmcnt(0)
	s_setprio 1
	s_barrier

	v_mfma_f32_16x16x32_bf16 v[62:65], v[146:149], v[178:181], v[62:65]
	v_mfma_f32_16x16x32_bf16 v[46:49], v[146:149], v[192:195], v[46:49]
	v_mfma_f32_16x16x32_bf16 v[30:33], v[146:149], v[200:203], v[30:33]
	v_mfma_f32_16x16x32_bf16 v[14:17], v[146:149], v[208:211], v[14:17]
	v_mfma_f32_16x16x32_bf16 v[54:57], v[154:157], v[178:181], v[54:57]
	v_mfma_f32_16x16x32_bf16 v[38:41], v[154:157], v[192:195], v[38:41]
	v_mfma_f32_16x16x32_bf16 v[22:25], v[154:157], v[200:203], v[22:25]
	v_mfma_f32_16x16x32_bf16 v[6:9], v[154:157], v[208:211], v[6:9]
	v_mfma_f32_16x16x32_bf16 v[62:65], v[150:153], v[182:185], v[62:65]
	v_mfma_f32_16x16x32_bf16 v[46:49], v[150:153], v[196:199], v[46:49]
	v_mfma_f32_16x16x32_bf16 v[30:33], v[150:153], v[204:207], v[30:33]
	v_mfma_f32_16x16x32_bf16 v[14:17], v[150:153], v[212:215], v[14:17]
	v_mfma_f32_16x16x32_bf16 v[54:57], v[158:161], v[182:185], v[54:57]
	v_mfma_f32_16x16x32_bf16 v[38:41], v[158:161], v[196:199], v[38:41]
	v_mfma_f32_16x16x32_bf16 v[22:25], v[158:161], v[204:207], v[22:25]
	v_mfma_f32_16x16x32_bf16 v[6:9], v[158:161], v[212:215], v[6:9]


	v_mfma_f32_16x16x32_bf16 v[58:61], v[162:165], v[178:181], v[58:61]
	v_mfma_f32_16x16x32_bf16 v[42:45], v[162:165], v[192:195], v[42:45]
	v_mfma_f32_16x16x32_bf16 v[26:29], v[162:165], v[200:203], v[26:29]
	v_mfma_f32_16x16x32_bf16 v[10:13], v[162:165], v[208:211], v[10:13]
	v_mfma_f32_16x16x32_bf16 v[50:53], v[170:173], v[178:181], v[50:53]
	v_mfma_f32_16x16x32_bf16 v[34:37], v[170:173], v[192:195], v[34:37]
	v_mfma_f32_16x16x32_bf16 v[18:21], v[170:173], v[200:203], v[18:21]
	v_mfma_f32_16x16x32_bf16 v[2:5], v[170:173], v[208:211], v[2:5]
	v_mfma_f32_16x16x32_bf16 v[58:61], v[166:169], v[182:185], v[58:61]
	v_mfma_f32_16x16x32_bf16 v[42:45], v[166:169], v[196:199], v[42:45]
	v_mfma_f32_16x16x32_bf16 v[26:29], v[166:169], v[204:207], v[26:29]
	v_mfma_f32_16x16x32_bf16 v[10:13], v[166:169], v[212:215], v[10:13]
	v_mfma_f32_16x16x32_bf16 v[50:53], v[174:177], v[182:185], v[50:53]
	v_mfma_f32_16x16x32_bf16 v[34:37], v[174:177], v[196:199], v[34:37]
	v_mfma_f32_16x16x32_bf16 v[18:21], v[174:177], v[204:207], v[18:21]
	v_mfma_f32_16x16x32_bf16 v[2:5], v[174:177], v[212:215], v[2:5]
	s_barrier
	s_setprio 0
	s_add_i32 s0, 0, 0x18000
	v_add_u32_e32 v145, s0, v143
	s_add_i32 s1, 0, 0x1c000
	ds_read_b128 v[146:149], v145
	ds_read_b128 v[150:153], v145 offset:1024
	ds_read_b128 v[154:157], v145 offset:2048
	ds_read_b128 v[158:161], v145 offset:3072
	v_add_u32_e32 v145, s1, v143
	ds_read_b128 v[162:165], v145
	ds_read_b128 v[166:169], v145 offset:1024
	ds_read_b128 v[170:173], v145 offset:2048
	ds_read_b128 v[174:177], v145 offset:3072
	s_add_u32 s26, s26, 0x80000
	s_addc_u32 s27, s27, 0
	s_mov_b32 m0, s37
	v_lshl_add_u64 v[222:223], s[26:27], 0, v[134:135]
	ds_read_b128 v[178:181], v144 offset:32768
	ds_read_b128 v[182:185], v144 offset:33792
	ds_read_b128 v[192:195], v144 offset:34816
	ds_read_b128 v[196:199], v144 offset:35840
	ds_read_b128 v[200:203], v144 offset:36864
	ds_read_b128 v[204:207], v144 offset:37888
	ds_read_b128 v[208:211], v144 offset:38912
	ds_read_b128 v[212:215], v144 offset:39936
	global_load_lds_dwordx4 v[222:223], off
	v_lshl_add_u64 v[222:223], s[26:27], 0, v[132:133]
	s_mov_b32 m0, s38
	s_nop 0
	global_load_lds_dwordx4 v[222:223], off
	s_waitcnt vmcnt(8)
	s_waitcnt lgkmcnt(0)
	s_setprio 1
	s_barrier

	v_mfma_f32_16x16x32_bf16 v[126:129], v[146:149], v[178:181], v[126:129]
	v_mfma_f32_16x16x32_bf16 v[110:113], v[146:149], v[192:195], v[110:113]
	v_mfma_f32_16x16x32_bf16 v[94:97], v[146:149], v[200:203], v[94:97]
	v_mfma_f32_16x16x32_bf16 v[78:81], v[146:149], v[208:211], v[78:81]
	v_mfma_f32_16x16x32_bf16 v[118:121], v[154:157], v[178:181], v[118:121]
	v_mfma_f32_16x16x32_bf16 v[102:105], v[154:157], v[192:195], v[102:105]
	v_mfma_f32_16x16x32_bf16 v[86:89], v[154:157], v[200:203], v[86:89]
	v_mfma_f32_16x16x32_bf16 v[70:73], v[154:157], v[208:211], v[70:73]
	v_mfma_f32_16x16x32_bf16 v[126:129], v[150:153], v[182:185], v[126:129]
	v_mfma_f32_16x16x32_bf16 v[110:113], v[150:153], v[196:199], v[110:113]
	v_mfma_f32_16x16x32_bf16 v[94:97], v[150:153], v[204:207], v[94:97]
	v_mfma_f32_16x16x32_bf16 v[78:81], v[150:153], v[212:215], v[78:81]
	v_mfma_f32_16x16x32_bf16 v[118:121], v[158:161], v[182:185], v[118:121]
	v_mfma_f32_16x16x32_bf16 v[102:105], v[158:161], v[196:199], v[102:105]
	v_mfma_f32_16x16x32_bf16 v[86:89], v[158:161], v[204:207], v[86:89]
	v_mfma_f32_16x16x32_bf16 v[70:73], v[158:161], v[212:215], v[70:73]


	v_mfma_f32_16x16x32_bf16 v[122:125], v[162:165], v[178:181], v[122:125]
	v_mfma_f32_16x16x32_bf16 v[106:109], v[162:165], v[192:195], v[106:109]
	v_mfma_f32_16x16x32_bf16 v[90:93], v[162:165], v[200:203], v[90:93]
	v_mfma_f32_16x16x32_bf16 v[74:77], v[162:165], v[208:211], v[74:77]
	v_mfma_f32_16x16x32_bf16 v[114:117], v[170:173], v[178:181], v[114:117]
	v_mfma_f32_16x16x32_bf16 v[98:101], v[170:173], v[192:195], v[98:101]
	v_mfma_f32_16x16x32_bf16 v[82:85], v[170:173], v[200:203], v[82:85]
	v_mfma_f32_16x16x32_bf16 v[66:69], v[170:173], v[208:211], v[66:69]
	v_mfma_f32_16x16x32_bf16 v[122:125], v[166:169], v[182:185], v[122:125]
	v_mfma_f32_16x16x32_bf16 v[106:109], v[166:169], v[196:199], v[106:109]
	v_mfma_f32_16x16x32_bf16 v[90:93], v[166:169], v[204:207], v[90:93]
	v_mfma_f32_16x16x32_bf16 v[74:77], v[166:169], v[212:215], v[74:77]
	v_mfma_f32_16x16x32_bf16 v[114:117], v[174:177], v[182:185], v[114:117]
	v_mfma_f32_16x16x32_bf16 v[98:101], v[174:177], v[196:199], v[98:101]
	v_mfma_f32_16x16x32_bf16 v[82:85], v[174:177], v[204:207], v[82:85]
	v_mfma_f32_16x16x32_bf16 v[66:69], v[174:177], v[212:215], v[66:69]
	s_barrier
	s_setprio 0
	s_add_i32 s0, s0, s31
	v_lshl_add_u64 v[140:141], v[140:141], 0, s[84:85]
	s_mov_b32 m0, s0
	ds_read_b128 v[178:181], v144 offset:49152
	ds_read_b128 v[182:185], v144 offset:50176
	ds_read_b128 v[192:195], v144 offset:51200
	ds_read_b128 v[196:199], v144 offset:52224
	ds_read_b128 v[200:203], v144 offset:53248
	ds_read_b128 v[204:207], v144 offset:54272
	ds_read_b128 v[208:211], v144 offset:55296
	ds_read_b128 v[212:215], v144 offset:56320
	global_load_lds_dwordx4 v[140:141], off
	s_add_i32 m0, s0, 0x2000
	s_add_u32 s24, s24, 0x80080
	v_lshl_add_u64 v[140:141], v[216:217], 0, s[84:85]
	s_addc_u32 s25, s25, 0
	s_add_i32 s0, s1, s31
	global_load_lds_dwordx4 v[140:141], off
	v_lshl_add_u64 v[140:141], s[24:25], 0, v[186:187]
	s_mov_b32 m0, s0
	s_nop 0
	global_load_lds_dwordx4 v[140:141], off
	v_lshl_add_u64 v[140:141], s[24:25], 0, v[130:131]
	s_add_i32 m0, s0, 0x2000
	s_nop 0
	global_load_lds_dwordx4 v[140:141], off
	v_lshl_add_u64 v[140:141], v[218:219], 0, s[84:85]
	s_mov_b32 m0, s39
	s_nop 0
	global_load_lds_dwordx4 v[140:141], off
	v_lshl_add_u64 v[140:141], v[220:221], 0, s[84:85]
	s_mov_b32 m0, s40
	s_nop 0
	global_load_lds_dwordx4 v[140:141], off
	s_waitcnt vmcnt(8)
	s_waitcnt lgkmcnt(0)
	s_setprio 1
	s_barrier

	v_mfma_f32_16x16x32_bf16 v[62:65], v[146:149], v[178:181], v[62:65]
	v_mfma_f32_16x16x32_bf16 v[46:49], v[146:149], v[192:195], v[46:49]
	v_mfma_f32_16x16x32_bf16 v[30:33], v[146:149], v[200:203], v[30:33]
	v_mfma_f32_16x16x32_bf16 v[14:17], v[146:149], v[208:211], v[14:17]
	v_mfma_f32_16x16x32_bf16 v[54:57], v[154:157], v[178:181], v[54:57]
	v_mfma_f32_16x16x32_bf16 v[38:41], v[154:157], v[192:195], v[38:41]
	v_mfma_f32_16x16x32_bf16 v[22:25], v[154:157], v[200:203], v[22:25]
	v_mfma_f32_16x16x32_bf16 v[6:9], v[154:157], v[208:211], v[6:9]
	v_mfma_f32_16x16x32_bf16 v[62:65], v[150:153], v[182:185], v[62:65]
	v_mfma_f32_16x16x32_bf16 v[46:49], v[150:153], v[196:199], v[46:49]
	v_mfma_f32_16x16x32_bf16 v[30:33], v[150:153], v[204:207], v[30:33]
	v_mfma_f32_16x16x32_bf16 v[14:17], v[150:153], v[212:215], v[14:17]
	v_mfma_f32_16x16x32_bf16 v[54:57], v[158:161], v[182:185], v[54:57]
	v_mfma_f32_16x16x32_bf16 v[38:41], v[158:161], v[196:199], v[38:41]
	v_mfma_f32_16x16x32_bf16 v[22:25], v[158:161], v[204:207], v[22:25]
	v_mfma_f32_16x16x32_bf16 v[6:9], v[158:161], v[212:215], v[6:9]


	v_mfma_f32_16x16x32_bf16 v[58:61], v[162:165], v[178:181], v[58:61]
	v_mfma_f32_16x16x32_bf16 v[42:45], v[162:165], v[192:195], v[42:45]
	v_mfma_f32_16x16x32_bf16 v[26:29], v[162:165], v[200:203], v[26:29]
	v_mfma_f32_16x16x32_bf16 v[10:13], v[162:165], v[208:211], v[10:13]
	v_mfma_f32_16x16x32_bf16 v[50:53], v[170:173], v[178:181], v[50:53]
	v_mfma_f32_16x16x32_bf16 v[34:37], v[170:173], v[192:195], v[34:37]
	v_mfma_f32_16x16x32_bf16 v[18:21], v[170:173], v[200:203], v[18:21]
	v_mfma_f32_16x16x32_bf16 v[2:5], v[170:173], v[208:211], v[2:5]
	v_mfma_f32_16x16x32_bf16 v[58:61], v[166:169], v[182:185], v[58:61]
	v_mfma_f32_16x16x32_bf16 v[42:45], v[166:169], v[196:199], v[42:45]
	v_mfma_f32_16x16x32_bf16 v[26:29], v[166:169], v[204:207], v[26:29]
	v_mfma_f32_16x16x32_bf16 v[10:13], v[166:169], v[212:215], v[10:13]
	v_mfma_f32_16x16x32_bf16 v[50:53], v[174:177], v[182:185], v[50:53]
	v_mfma_f32_16x16x32_bf16 v[34:37], v[174:177], v[196:199], v[34:37]
	v_mfma_f32_16x16x32_bf16 v[18:21], v[174:177], v[204:207], v[18:21]
	v_mfma_f32_16x16x32_bf16 v[2:5], v[174:177], v[212:215], v[2:5]
	s_barrier
	s_setprio 0
	s_add_i32 s50, s50, 2
	s_add_u32 s22, s22, 0x100
	s_addc_u32 s23, s23, 0
	s_add_u32 s48, s48, 0x100
	s_addc_u32 s49, s49, 0
	s_cmp_gt_u32 s50, 29
	s_cbranch_scc0 .LBB0_159
	s_and_b64 vcc, exec, s[10:11]
	s_cbranch_vccz .LBB0_162
	s_barrier

.LBB0_243:
	s_add_u32 s22, s20, 0x100
	s_addc_u32 s23, s21, 0
	s_add_i32 s0, 0, 0x10000
	s_cmpk_eq_i32 s51, 0x54
	s_cselect_b32 s27, s7, s23
	s_cselect_b32 s26, s6, s22
	s_cselect_b32 s25, s19, s50
	s_cselect_b32 s24, s18, s49
	s_add_i32 s1, 0, 0x14000
	v_add_u32_e32 v126, s0, v237
	v_add_u32_e32 v158, s1, v237
	ds_read_b128 v[90:93], v126
	ds_read_b128 v[102:105], v126 offset:1024
	ds_read_b128 v[114:117], v126 offset:2048
	ds_read_b128 v[126:129], v126 offset:3072
	ds_read_b128 v[138:141], v158
	ds_read_b128 v[142:145], v158 offset:1024
	ds_read_b128 v[154:157], v158 offset:2048
	ds_read_b128 v[158:161], v158 offset:3072
	v_lshl_add_u64 v[210:211], s[20:21], 0, v[198:199]
	s_add_i32 m0, s34, 0xc000
	ds_read_b128 v[162:165], v238
	ds_read_b128 v[166:169], v238 offset:1024
	ds_read_b128 v[170:173], v238 offset:2048
	ds_read_b128 v[174:177], v238 offset:3072
	ds_read_b128 v[178:181], v238 offset:4096
	ds_read_b128 v[182:185], v238 offset:5120
	ds_read_b128 v[202:205], v238 offset:6144
	ds_read_b128 v[206:209], v238 offset:7168
	global_load_lds_dwordx4 v[210:211], off
	v_lshl_add_u64 v[210:211], s[20:21], 0, v[200:201]
	s_add_i32 m0, s34, 0xe000
	s_nop 0
	global_load_lds_dwordx4 v[210:211], off
	s_waitcnt vmcnt(8)
	s_waitcnt lgkmcnt(0)
	s_setprio 1
	s_barrier

	v_mfma_f32_16x16x32_bf16 v[150:153], v[90:93], v[162:165], v[150:153]
	v_mfma_f32_16x16x32_bf16 v[122:125], v[90:93], v[170:173], v[122:125]
	v_mfma_f32_16x16x32_bf16 v[98:101], v[90:93], v[178:181], v[98:101]
	v_mfma_f32_16x16x32_bf16 v[78:81], v[90:93], v[202:205], v[78:81]
	v_mfma_f32_16x16x32_bf16 v[146:149], v[114:117], v[162:165], v[146:149]
	v_mfma_f32_16x16x32_bf16 v[118:121], v[114:117], v[170:173], v[118:121]
	v_mfma_f32_16x16x32_bf16 v[94:97], v[114:117], v[178:181], v[94:97]
	v_mfma_f32_16x16x32_bf16 v[74:77], v[114:117], v[202:205], v[74:77]
	v_mfma_f32_16x16x32_bf16 v[150:153], v[102:105], v[166:169], v[150:153]
	v_mfma_f32_16x16x32_bf16 v[122:125], v[102:105], v[174:177], v[122:125]
	v_mfma_f32_16x16x32_bf16 v[98:101], v[102:105], v[182:185], v[98:101]
	v_mfma_f32_16x16x32_bf16 v[78:81], v[102:105], v[206:209], v[78:81]
	v_mfma_f32_16x16x32_bf16 v[146:149], v[126:129], v[166:169], v[146:149]
	v_mfma_f32_16x16x32_bf16 v[118:121], v[126:129], v[174:177], v[118:121]
	v_mfma_f32_16x16x32_bf16 v[94:97], v[126:129], v[182:185], v[94:97]
	v_mfma_f32_16x16x32_bf16 v[74:77], v[126:129], v[206:209], v[74:77]


	v_mfma_f32_16x16x32_bf16 v[134:137], v[138:141], v[162:165], v[134:137]
	v_mfma_f32_16x16x32_bf16 v[110:113], v[138:141], v[170:173], v[110:113]
	v_mfma_f32_16x16x32_bf16 v[86:89], v[138:141], v[178:181], v[86:89]
	v_mfma_f32_16x16x32_bf16 v[70:73], v[138:141], v[202:205], v[70:73]
	v_mfma_f32_16x16x32_bf16 v[130:133], v[154:157], v[162:165], v[130:133]
	v_mfma_f32_16x16x32_bf16 v[106:109], v[154:157], v[170:173], v[106:109]
	v_mfma_f32_16x16x32_bf16 v[82:85], v[154:157], v[178:181], v[82:85]
	v_mfma_f32_16x16x32_bf16 v[66:69], v[154:157], v[202:205], v[66:69]
	v_mfma_f32_16x16x32_bf16 v[134:137], v[142:145], v[166:169], v[134:137]
	v_mfma_f32_16x16x32_bf16 v[110:113], v[142:145], v[174:177], v[110:113]
	v_mfma_f32_16x16x32_bf16 v[86:89], v[142:145], v[182:185], v[86:89]
	v_mfma_f32_16x16x32_bf16 v[70:73], v[142:145], v[206:209], v[70:73]
	v_mfma_f32_16x16x32_bf16 v[130:133], v[158:161], v[166:169], v[130:133]
	v_mfma_f32_16x16x32_bf16 v[106:109], v[158:161], v[174:177], v[106:109]
	v_mfma_f32_16x16x32_bf16 v[82:85], v[158:161], v[182:185], v[82:85]
	v_mfma_f32_16x16x32_bf16 v[66:69], v[158:161], v[206:209], v[66:69]
	s_barrier
	s_setprio 0
	s_add_i32 s0, s0, s31
	v_lshl_add_u64 v[210:211], s[24:25], 0, v[186:187]
	s_mov_b32 m0, s0
	ds_read_b128 v[162:165], v238 offset:16384
	ds_read_b128 v[166:169], v238 offset:17408
	ds_read_b128 v[170:173], v238 offset:18432
	ds_read_b128 v[174:177], v238 offset:19456
	ds_read_b128 v[178:181], v238 offset:20480
	ds_read_b128 v[182:185], v238 offset:21504
	ds_read_b128 v[202:205], v238 offset:22528
	ds_read_b128 v[206:209], v238 offset:23552
	global_load_lds_dwordx4 v[210:211], off
	s_add_i32 m0, s0, 0x2000
	s_add_u32 s20, s24, 0x160000
	v_lshl_add_u64 v[212:213], s[24:25], 0, v[196:197]
	s_addc_u32 s21, s25, 0
	s_add_i32 s0, s1, s31
	global_load_lds_dwordx4 v[212:213], off
	v_lshl_add_u64 v[214:215], s[20:21], 0, v[186:187]
	s_mov_b32 m0, s0
	v_lshl_add_u64 v[216:217], s[26:27], 0, v[194:195]
	global_load_lds_dwordx4 v[214:215], off
	v_lshl_add_u64 v[214:215], s[20:21], 0, v[196:197]
	s_add_i32 m0, s0, 0x2000
	s_nop 0
	global_load_lds_dwordx4 v[214:215], off
	v_lshl_add_u64 v[214:215], s[26:27], 0, v[192:193]
	s_mov_b32 m0, s34
	s_nop 0
	global_load_lds_dwordx4 v[214:215], off
	s_mov_b32 m0, s35
	s_nop 0
	global_load_lds_dwordx4 v[216:217], off
	s_waitcnt vmcnt(8)
	s_waitcnt lgkmcnt(0)
	s_setprio 1
	s_barrier

	v_mfma_f32_16x16x32_bf16 v[62:65], v[90:93], v[162:165], v[62:65]
	v_mfma_f32_16x16x32_bf16 v[46:49], v[90:93], v[170:173], v[46:49]
	v_mfma_f32_16x16x32_bf16 v[30:33], v[90:93], v[178:181], v[30:33]
	v_mfma_f32_16x16x32_bf16 v[14:17], v[90:93], v[202:205], v[14:17]
	v_mfma_f32_16x16x32_bf16 v[58:61], v[114:117], v[162:165], v[58:61]
	v_mfma_f32_16x16x32_bf16 v[42:45], v[114:117], v[170:173], v[42:45]
	v_mfma_f32_16x16x32_bf16 v[26:29], v[114:117], v[178:181], v[26:29]
	v_mfma_f32_16x16x32_bf16 v[10:13], v[114:117], v[202:205], v[10:13]
	v_mfma_f32_16x16x32_bf16 v[62:65], v[102:105], v[166:169], v[62:65]
	v_mfma_f32_16x16x32_bf16 v[46:49], v[102:105], v[174:177], v[46:49]
	v_mfma_f32_16x16x32_bf16 v[30:33], v[102:105], v[182:185], v[30:33]
	v_mfma_f32_16x16x32_bf16 v[14:17], v[102:105], v[206:209], v[14:17]
	v_mfma_f32_16x16x32_bf16 v[58:61], v[126:129], v[166:169], v[58:61]
	v_mfma_f32_16x16x32_bf16 v[42:45], v[126:129], v[174:177], v[42:45]
	v_mfma_f32_16x16x32_bf16 v[26:29], v[126:129], v[182:185], v[26:29]
	v_mfma_f32_16x16x32_bf16 v[10:13], v[126:129], v[206:209], v[10:13]


	v_mfma_f32_16x16x32_bf16 v[54:57], v[138:141], v[162:165], v[54:57]
	v_mfma_f32_16x16x32_bf16 v[38:41], v[138:141], v[170:173], v[38:41]
	v_mfma_f32_16x16x32_bf16 v[22:25], v[138:141], v[178:181], v[22:25]
	v_mfma_f32_16x16x32_bf16 v[6:9], v[138:141], v[202:205], v[6:9]
	v_mfma_f32_16x16x32_bf16 v[50:53], v[154:157], v[162:165], v[50:53]
	v_mfma_f32_16x16x32_bf16 v[34:37], v[154:157], v[170:173], v[34:37]
	v_mfma_f32_16x16x32_bf16 v[18:21], v[154:157], v[178:181], v[18:21]
	v_mfma_f32_16x16x32_bf16 v[2:5], v[154:157], v[202:205], v[2:5]
	v_mfma_f32_16x16x32_bf16 v[54:57], v[142:145], v[166:169], v[54:57]
	v_mfma_f32_16x16x32_bf16 v[38:41], v[142:145], v[174:177], v[38:41]
	v_mfma_f32_16x16x32_bf16 v[22:25], v[142:145], v[182:185], v[22:25]
	v_mfma_f32_16x16x32_bf16 v[6:9], v[142:145], v[206:209], v[6:9]
	v_mfma_f32_16x16x32_bf16 v[50:53], v[158:161], v[166:169], v[50:53]
	v_mfma_f32_16x16x32_bf16 v[34:37], v[158:161], v[174:177], v[34:37]
	v_mfma_f32_16x16x32_bf16 v[18:21], v[158:161], v[182:185], v[18:21]
	v_mfma_f32_16x16x32_bf16 v[2:5], v[158:161], v[206:209], v[2:5]
	s_barrier
	s_setprio 0
	s_add_i32 s0, 0, 0x18000
	s_add_i32 s1, 0, 0x1c000
	v_add_u32_e32 v126, s0, v237
	v_add_u32_e32 v158, s1, v237
	ds_read_b128 v[90:93], v126
	ds_read_b128 v[102:105], v126 offset:1024
	ds_read_b128 v[114:117], v126 offset:2048
	ds_read_b128 v[126:129], v126 offset:3072
	ds_read_b128 v[138:141], v158
	ds_read_b128 v[142:145], v158 offset:1024
	ds_read_b128 v[154:157], v158 offset:2048
	ds_read_b128 v[158:161], v158 offset:3072
	s_add_u32 s20, s26, 0x160000
	s_addc_u32 s21, s27, 0
	s_mov_b32 m0, s36
	v_lshl_add_u64 v[218:219], s[20:21], 0, v[192:193]
	ds_read_b128 v[162:165], v238 offset:32768
	ds_read_b128 v[166:169], v238 offset:33792
	ds_read_b128 v[170:173], v238 offset:34816
	ds_read_b128 v[174:177], v238 offset:35840
	ds_read_b128 v[178:181], v238 offset:36864
	ds_read_b128 v[182:185], v238 offset:37888
	ds_read_b128 v[202:205], v238 offset:38912
	ds_read_b128 v[206:209], v238 offset:39936
	global_load_lds_dwordx4 v[218:219], off
	v_lshl_add_u64 v[218:219], s[20:21], 0, v[194:195]
	s_mov_b32 m0, s37
	s_nop 0
	global_load_lds_dwordx4 v[218:219], off
	s_waitcnt vmcnt(8)
	s_waitcnt lgkmcnt(0)
	s_setprio 1
	s_barrier

	v_mfma_f32_16x16x32_bf16 v[150:153], v[90:93], v[162:165], v[150:153]
	v_mfma_f32_16x16x32_bf16 v[122:125], v[90:93], v[170:173], v[122:125]
	v_mfma_f32_16x16x32_bf16 v[98:101], v[90:93], v[178:181], v[98:101]
	v_mfma_f32_16x16x32_bf16 v[78:81], v[90:93], v[202:205], v[78:81]
	v_mfma_f32_16x16x32_bf16 v[146:149], v[114:117], v[162:165], v[146:149]
	v_mfma_f32_16x16x32_bf16 v[118:121], v[114:117], v[170:173], v[118:121]
	v_mfma_f32_16x16x32_bf16 v[94:97], v[114:117], v[178:181], v[94:97]
	v_mfma_f32_16x16x32_bf16 v[74:77], v[114:117], v[202:205], v[74:77]
	v_mfma_f32_16x16x32_bf16 v[150:153], v[102:105], v[166:169], v[150:153]
	v_mfma_f32_16x16x32_bf16 v[122:125], v[102:105], v[174:177], v[122:125]
	v_mfma_f32_16x16x32_bf16 v[98:101], v[102:105], v[182:185], v[98:101]
	v_mfma_f32_16x16x32_bf16 v[78:81], v[102:105], v[206:209], v[78:81]
	v_mfma_f32_16x16x32_bf16 v[146:149], v[126:129], v[166:169], v[146:149]
	v_mfma_f32_16x16x32_bf16 v[118:121], v[126:129], v[174:177], v[118:121]
	v_mfma_f32_16x16x32_bf16 v[94:97], v[126:129], v[182:185], v[94:97]
	v_mfma_f32_16x16x32_bf16 v[74:77], v[126:129], v[206:209], v[74:77]


	v_mfma_f32_16x16x32_bf16 v[134:137], v[138:141], v[162:165], v[134:137]
	v_mfma_f32_16x16x32_bf16 v[110:113], v[138:141], v[170:173], v[110:113]
	v_mfma_f32_16x16x32_bf16 v[86:89], v[138:141], v[178:181], v[86:89]
	v_mfma_f32_16x16x32_bf16 v[70:73], v[138:141], v[202:205], v[70:73]
	v_mfma_f32_16x16x32_bf16 v[130:133], v[154:157], v[162:165], v[130:133]
	v_mfma_f32_16x16x32_bf16 v[106:109], v[154:157], v[170:173], v[106:109]
	v_mfma_f32_16x16x32_bf16 v[82:85], v[154:157], v[178:181], v[82:85]
	v_mfma_f32_16x16x32_bf16 v[66:69], v[154:157], v[202:205], v[66:69]
	v_mfma_f32_16x16x32_bf16 v[134:137], v[142:145], v[166:169], v[134:137]
	v_mfma_f32_16x16x32_bf16 v[110:113], v[142:145], v[174:177], v[110:113]
	v_mfma_f32_16x16x32_bf16 v[86:89], v[142:145], v[182:185], v[86:89]
	v_mfma_f32_16x16x32_bf16 v[70:73], v[142:145], v[206:209], v[70:73]
	v_mfma_f32_16x16x32_bf16 v[130:133], v[158:161], v[166:169], v[130:133]
	v_mfma_f32_16x16x32_bf16 v[106:109], v[158:161], v[174:177], v[106:109]
	v_mfma_f32_16x16x32_bf16 v[82:85], v[158:161], v[182:185], v[82:85]
	v_mfma_f32_16x16x32_bf16 v[66:69], v[158:161], v[206:209], v[66:69]
	s_barrier
	s_setprio 0
	s_add_i32 s0, s0, s31
	v_lshl_add_u64 v[210:211], v[210:211], 0, s[84:85]
	s_mov_b32 m0, s0
	ds_read_b128 v[162:165], v238 offset:49152
	ds_read_b128 v[166:169], v238 offset:50176
	ds_read_b128 v[170:173], v238 offset:51200
	ds_read_b128 v[174:177], v238 offset:52224
	ds_read_b128 v[178:181], v238 offset:53248
	ds_read_b128 v[182:185], v238 offset:54272
	ds_read_b128 v[202:205], v238 offset:55296
	ds_read_b128 v[206:209], v238 offset:56320
	global_load_lds_dwordx4 v[210:211], off
	s_add_i32 m0, s0, 0x2000
	s_add_u32 s20, s24, 0x160080
	v_lshl_add_u64 v[210:211], v[212:213], 0, s[84:85]
	s_addc_u32 s21, s25, 0
	s_add_i32 s0, s1, s31
	global_load_lds_dwordx4 v[210:211], off
	v_lshl_add_u64 v[210:211], s[20:21], 0, v[186:187]
	s_mov_b32 m0, s0
	s_nop 0
	global_load_lds_dwordx4 v[210:211], off
	v_lshl_add_u64 v[210:211], s[20:21], 0, v[196:197]
	s_add_i32 m0, s0, 0x2000
	s_nop 0
	global_load_lds_dwordx4 v[210:211], off
	v_lshl_add_u64 v[210:211], v[214:215], 0, s[84:85]
	s_mov_b32 m0, s41
	s_nop 0
	global_load_lds_dwordx4 v[210:211], off
	v_lshl_add_u64 v[210:211], v[216:217], 0, s[84:85]
	s_mov_b32 m0, s42
	s_nop 0
	global_load_lds_dwordx4 v[210:211], off
	s_waitcnt vmcnt(8)
	s_waitcnt lgkmcnt(0)
	s_setprio 1
	s_barrier

	v_mfma_f32_16x16x32_bf16 v[62:65], v[90:93], v[162:165], v[62:65]
	v_mfma_f32_16x16x32_bf16 v[46:49], v[90:93], v[170:173], v[46:49]
	v_mfma_f32_16x16x32_bf16 v[30:33], v[90:93], v[178:181], v[30:33]
	v_mfma_f32_16x16x32_bf16 v[14:17], v[90:93], v[202:205], v[14:17]
	v_mfma_f32_16x16x32_bf16 v[58:61], v[114:117], v[162:165], v[58:61]
	v_mfma_f32_16x16x32_bf16 v[42:45], v[114:117], v[170:173], v[42:45]
	v_mfma_f32_16x16x32_bf16 v[26:29], v[114:117], v[178:181], v[26:29]
	v_mfma_f32_16x16x32_bf16 v[10:13], v[114:117], v[202:205], v[10:13]
	v_mfma_f32_16x16x32_bf16 v[62:65], v[102:105], v[166:169], v[62:65]
	v_mfma_f32_16x16x32_bf16 v[46:49], v[102:105], v[174:177], v[46:49]
	v_mfma_f32_16x16x32_bf16 v[30:33], v[102:105], v[182:185], v[30:33]
	v_mfma_f32_16x16x32_bf16 v[14:17], v[102:105], v[206:209], v[14:17]
	v_mfma_f32_16x16x32_bf16 v[58:61], v[126:129], v[166:169], v[58:61]
	v_mfma_f32_16x16x32_bf16 v[42:45], v[126:129], v[174:177], v[42:45]
	v_mfma_f32_16x16x32_bf16 v[26:29], v[126:129], v[182:185], v[26:29]
	v_mfma_f32_16x16x32_bf16 v[10:13], v[126:129], v[206:209], v[10:13]


	v_mfma_f32_16x16x32_bf16 v[54:57], v[138:141], v[162:165], v[54:57]
	v_mfma_f32_16x16x32_bf16 v[38:41], v[138:141], v[170:173], v[38:41]
	v_mfma_f32_16x16x32_bf16 v[22:25], v[138:141], v[178:181], v[22:25]
	v_mfma_f32_16x16x32_bf16 v[6:9], v[138:141], v[202:205], v[6:9]
	v_mfma_f32_16x16x32_bf16 v[50:53], v[154:157], v[162:165], v[50:53]
	v_mfma_f32_16x16x32_bf16 v[34:37], v[154:157], v[170:173], v[34:37]
	v_mfma_f32_16x16x32_bf16 v[18:21], v[154:157], v[178:181], v[18:21]
	v_mfma_f32_16x16x32_bf16 v[2:5], v[154:157], v[202:205], v[2:5]
	v_mfma_f32_16x16x32_bf16 v[54:57], v[142:145], v[166:169], v[54:57]
	v_mfma_f32_16x16x32_bf16 v[38:41], v[142:145], v[174:177], v[38:41]
	v_mfma_f32_16x16x32_bf16 v[22:25], v[142:145], v[182:185], v[22:25]
	v_mfma_f32_16x16x32_bf16 v[6:9], v[142:145], v[206:209], v[6:9]
	v_mfma_f32_16x16x32_bf16 v[50:53], v[158:161], v[166:169], v[50:53]
	v_mfma_f32_16x16x32_bf16 v[34:37], v[158:161], v[174:177], v[34:37]
	v_mfma_f32_16x16x32_bf16 v[18:21], v[158:161], v[182:185], v[18:21]
	v_mfma_f32_16x16x32_bf16 v[2:5], v[158:161], v[206:209], v[2:5]
	s_barrier
	s_setprio 0
	s_add_i32 s51, s51, 2
	s_add_u32 s49, s49, 0x100
	s_addc_u32 s50, s50, 0
	s_cmpk_gt_u32 s51, 0x55
	s_mov_b64 s[20:21], s[22:23]
	s_cbranch_scc0 .LBB0_243
	s_and_b64 vcc, exec, s[16:17]
	s_cbranch_vccz .LBB0_246
	s_barrier

.LBB0_443:
	s_add_u32 s0, s26, 0xfff80080
	s_addc_u32 s1, s27, -1
	s_add_i32 s56, 0, 0x10000
	s_cmp_eq_u32 s55, 28
	s_cselect_b32 s31, s19, s1
	s_cselect_b32 s30, s51, s0
	v_add_u32_e32 v140, s56, v144
	s_cselect_b32 s29, s17, s54
	s_cselect_b32 s28, s52, s53
	s_add_i32 s0, 0, 0x14000
	ds_read_b128 v[146:149], v140
	ds_read_b128 v[150:153], v140 offset:1024
	ds_read_b128 v[154:157], v140 offset:2048
	ds_read_b128 v[158:161], v140 offset:3072
	v_add_u32_e32 v140, s0, v144
	ds_read_b128 v[162:165], v140
	ds_read_b128 v[166:169], v140 offset:1024
	ds_read_b128 v[170:173], v140 offset:2048
	ds_read_b128 v[174:177], v140 offset:3072
	v_lshl_add_u64 v[140:141], s[26:27], 0, v[136:137]
	s_add_i32 m0, s25, 0xc000
	ds_read_b128 v[178:181], v145
	ds_read_b128 v[182:185], v145 offset:1024
	ds_read_b128 v[192:195], v145 offset:2048
	ds_read_b128 v[196:199], v145 offset:3072
	ds_read_b128 v[200:203], v145 offset:4096
	ds_read_b128 v[204:207], v145 offset:5120
	ds_read_b128 v[208:211], v145 offset:6144
	ds_read_b128 v[212:215], v145 offset:7168
	global_load_lds_dwordx4 v[140:141], off
	v_lshl_add_u64 v[140:141], s[26:27], 0, v[138:139]
	s_add_i32 m0, s25, 0xe000
	s_nop 0
	global_load_lds_dwordx4 v[140:141], off
	s_waitcnt vmcnt(8)
	s_waitcnt lgkmcnt(0)
	s_setprio 1
	s_barrier

	v_mfma_f32_16x16x32_bf16 v[126:129], v[146:149], v[178:181], v[126:129]
	v_mfma_f32_16x16x32_bf16 v[114:117], v[146:149], v[192:195], v[114:117]
	v_mfma_f32_16x16x32_bf16 v[98:101], v[146:149], v[200:203], v[98:101]
	v_mfma_f32_16x16x32_bf16 v[82:85], v[146:149], v[208:211], v[82:85]
	v_mfma_f32_16x16x32_bf16 v[122:125], v[154:157], v[178:181], v[122:125]
	v_mfma_f32_16x16x32_bf16 v[106:109], v[154:157], v[192:195], v[106:109]
	v_mfma_f32_16x16x32_bf16 v[90:93], v[154:157], v[200:203], v[90:93]
	v_mfma_f32_16x16x32_bf16 v[74:77], v[154:157], v[208:211], v[74:77]
	v_mfma_f32_16x16x32_bf16 v[126:129], v[150:153], v[182:185], v[126:129]
	v_mfma_f32_16x16x32_bf16 v[114:117], v[150:153], v[196:199], v[114:117]
	v_mfma_f32_16x16x32_bf16 v[98:101], v[150:153], v[204:207], v[98:101]
	v_mfma_f32_16x16x32_bf16 v[82:85], v[150:153], v[212:215], v[82:85]
	v_mfma_f32_16x16x32_bf16 v[122:125], v[158:161], v[182:185], v[122:125]
	v_mfma_f32_16x16x32_bf16 v[106:109], v[158:161], v[196:199], v[106:109]
	v_mfma_f32_16x16x32_bf16 v[90:93], v[158:161], v[204:207], v[90:93]
	v_mfma_f32_16x16x32_bf16 v[74:77], v[158:161], v[212:215], v[74:77]


	v_mfma_f32_16x16x32_bf16 v[118:121], v[162:165], v[178:181], v[118:121]
	v_mfma_f32_16x16x32_bf16 v[102:105], v[162:165], v[192:195], v[102:105]
	v_mfma_f32_16x16x32_bf16 v[86:89], v[162:165], v[200:203], v[86:89]
	v_mfma_f32_16x16x32_bf16 v[70:73], v[162:165], v[208:211], v[70:73]
	v_mfma_f32_16x16x32_bf16 v[110:113], v[170:173], v[178:181], v[110:113]
	v_mfma_f32_16x16x32_bf16 v[94:97], v[170:173], v[192:195], v[94:97]
	v_mfma_f32_16x16x32_bf16 v[78:81], v[170:173], v[200:203], v[78:81]
	v_mfma_f32_16x16x32_bf16 v[66:69], v[170:173], v[208:211], v[66:69]
	v_mfma_f32_16x16x32_bf16 v[118:121], v[166:169], v[182:185], v[118:121]
	v_mfma_f32_16x16x32_bf16 v[102:105], v[166:169], v[196:199], v[102:105]
	v_mfma_f32_16x16x32_bf16 v[86:89], v[166:169], v[204:207], v[86:89]
	v_mfma_f32_16x16x32_bf16 v[70:73], v[166:169], v[212:215], v[70:73]
	v_mfma_f32_16x16x32_bf16 v[110:113], v[174:177], v[182:185], v[110:113]
	v_mfma_f32_16x16x32_bf16 v[94:97], v[174:177], v[196:199], v[94:97]
	v_mfma_f32_16x16x32_bf16 v[78:81], v[174:177], v[204:207], v[78:81]
	v_mfma_f32_16x16x32_bf16 v[66:69], v[174:177], v[212:215], v[66:69]
	s_barrier
	s_setprio 0
	s_add_i32 s1, s56, s39
	v_lshl_add_u64 v[140:141], s[28:29], 0, v[186:187]
	s_mov_b32 m0, s1
	ds_read_b128 v[178:181], v145 offset:16384
	ds_read_b128 v[182:185], v145 offset:17408
	ds_read_b128 v[192:195], v145 offset:18432
	ds_read_b128 v[196:199], v145 offset:19456
	ds_read_b128 v[200:203], v145 offset:20480
	ds_read_b128 v[204:207], v145 offset:21504
	ds_read_b128 v[208:211], v145 offset:22528
	ds_read_b128 v[212:215], v145 offset:23552
	global_load_lds_dwordx4 v[140:141], off
	s_add_i32 m0, s1, 0x2000
	s_add_u32 s56, s28, 0x80000
	v_lshl_add_u64 v[188:189], s[28:29], 0, v[130:131]
	s_addc_u32 s57, s29, 0
	s_add_i32 s0, s0, s39
	global_load_lds_dwordx4 v[188:189], off
	v_lshl_add_u64 v[216:217], s[56:57], 0, v[186:187]
	s_mov_b32 m0, s0
	v_lshl_add_u64 v[218:219], s[30:31], 0, v[132:133]
	global_load_lds_dwordx4 v[216:217], off
	v_lshl_add_u64 v[216:217], s[56:57], 0, v[130:131]
	s_add_i32 m0, s0, 0x2000
	s_nop 0
	global_load_lds_dwordx4 v[216:217], off
	v_lshl_add_u64 v[216:217], s[30:31], 0, v[134:135]
	s_mov_b32 m0, s25
	s_nop 0
	global_load_lds_dwordx4 v[216:217], off
	s_mov_b32 m0, s40
	s_nop 0
	global_load_lds_dwordx4 v[218:219], off
	s_waitcnt vmcnt(8)
	s_waitcnt lgkmcnt(0)
	s_setprio 1
	s_barrier

	v_mfma_f32_16x16x32_bf16 v[62:65], v[146:149], v[178:181], v[62:65]
	v_mfma_f32_16x16x32_bf16 v[50:53], v[146:149], v[192:195], v[50:53]
	v_mfma_f32_16x16x32_bf16 v[34:37], v[146:149], v[200:203], v[34:37]
	v_mfma_f32_16x16x32_bf16 v[18:21], v[146:149], v[208:211], v[18:21]
	v_mfma_f32_16x16x32_bf16 v[58:61], v[154:157], v[178:181], v[58:61]
	v_mfma_f32_16x16x32_bf16 v[42:45], v[154:157], v[192:195], v[42:45]
	v_mfma_f32_16x16x32_bf16 v[26:29], v[154:157], v[200:203], v[26:29]
	v_mfma_f32_16x16x32_bf16 v[10:13], v[154:157], v[208:211], v[10:13]
	v_mfma_f32_16x16x32_bf16 v[62:65], v[150:153], v[182:185], v[62:65]
	v_mfma_f32_16x16x32_bf16 v[50:53], v[150:153], v[196:199], v[50:53]
	v_mfma_f32_16x16x32_bf16 v[34:37], v[150:153], v[204:207], v[34:37]
	v_mfma_f32_16x16x32_bf16 v[18:21], v[150:153], v[212:215], v[18:21]
	v_mfma_f32_16x16x32_bf16 v[58:61], v[158:161], v[182:185], v[58:61]
	v_mfma_f32_16x16x32_bf16 v[42:45], v[158:161], v[196:199], v[42:45]
	v_mfma_f32_16x16x32_bf16 v[26:29], v[158:161], v[204:207], v[26:29]
	v_mfma_f32_16x16x32_bf16 v[10:13], v[158:161], v[212:215], v[10:13]


	v_mfma_f32_16x16x32_bf16 v[54:57], v[162:165], v[178:181], v[54:57]
	v_mfma_f32_16x16x32_bf16 v[38:41], v[162:165], v[192:195], v[38:41]
	v_mfma_f32_16x16x32_bf16 v[22:25], v[162:165], v[200:203], v[22:25]
	v_mfma_f32_16x16x32_bf16 v[6:9], v[162:165], v[208:211], v[6:9]
	v_mfma_f32_16x16x32_bf16 v[46:49], v[170:173], v[178:181], v[46:49]
	v_mfma_f32_16x16x32_bf16 v[30:33], v[170:173], v[192:195], v[30:33]
	v_mfma_f32_16x16x32_bf16 v[14:17], v[170:173], v[200:203], v[14:17]
	v_mfma_f32_16x16x32_bf16 v[2:5], v[170:173], v[208:211], v[2:5]
	v_mfma_f32_16x16x32_bf16 v[54:57], v[166:169], v[182:185], v[54:57]
	v_mfma_f32_16x16x32_bf16 v[38:41], v[166:169], v[196:199], v[38:41]
	v_mfma_f32_16x16x32_bf16 v[22:25], v[166:169], v[204:207], v[22:25]
	v_mfma_f32_16x16x32_bf16 v[6:9], v[166:169], v[212:215], v[6:9]
	v_mfma_f32_16x16x32_bf16 v[46:49], v[174:177], v[182:185], v[46:49]
	v_mfma_f32_16x16x32_bf16 v[30:33], v[174:177], v[196:199], v[30:33]
	v_mfma_f32_16x16x32_bf16 v[14:17], v[174:177], v[204:207], v[14:17]
	v_mfma_f32_16x16x32_bf16 v[2:5], v[174:177], v[212:215], v[2:5]
	s_barrier
	s_setprio 0
	s_add_i32 s0, 0, 0x18000
	s_add_i32 s1, 0, 0x1c000
	v_add_u32_e32 v158, s0, v144
	v_add_u32_e32 v174, s1, v144
	ds_read_b128 v[146:149], v158
	ds_read_b128 v[150:153], v158 offset:1024
	ds_read_b128 v[154:157], v158 offset:2048
	ds_read_b128 v[158:161], v158 offset:3072
	ds_read_b128 v[162:165], v174
	ds_read_b128 v[166:169], v174 offset:1024
	ds_read_b128 v[170:173], v174 offset:2048
	ds_read_b128 v[174:177], v174 offset:3072
	s_add_u32 s30, s30, 0x80000
	s_addc_u32 s31, s31, 0
	s_mov_b32 m0, s41
	v_lshl_add_u64 v[220:221], s[30:31], 0, v[134:135]
	ds_read_b128 v[178:181], v145 offset:32768
	ds_read_b128 v[182:185], v145 offset:33792
	ds_read_b128 v[192:195], v145 offset:34816
	ds_read_b128 v[196:199], v145 offset:35840
	ds_read_b128 v[200:203], v145 offset:36864
	ds_read_b128 v[204:207], v145 offset:37888
	ds_read_b128 v[208:211], v145 offset:38912
	ds_read_b128 v[212:215], v145 offset:39936
	global_load_lds_dwordx4 v[220:221], off
	v_lshl_add_u64 v[220:221], s[30:31], 0, v[132:133]
	s_mov_b32 m0, s42
	s_nop 0
	global_load_lds_dwordx4 v[220:221], off
	s_waitcnt vmcnt(8)
	s_waitcnt lgkmcnt(0)
	s_setprio 1
	s_barrier

	v_mfma_f32_16x16x32_bf16 v[126:129], v[146:149], v[178:181], v[126:129]
	v_mfma_f32_16x16x32_bf16 v[114:117], v[146:149], v[192:195], v[114:117]
	v_mfma_f32_16x16x32_bf16 v[98:101], v[146:149], v[200:203], v[98:101]
	v_mfma_f32_16x16x32_bf16 v[82:85], v[146:149], v[208:211], v[82:85]
	v_mfma_f32_16x16x32_bf16 v[122:125], v[154:157], v[178:181], v[122:125]
	v_mfma_f32_16x16x32_bf16 v[106:109], v[154:157], v[192:195], v[106:109]
	v_mfma_f32_16x16x32_bf16 v[90:93], v[154:157], v[200:203], v[90:93]
	v_mfma_f32_16x16x32_bf16 v[74:77], v[154:157], v[208:211], v[74:77]
	v_mfma_f32_16x16x32_bf16 v[126:129], v[150:153], v[182:185], v[126:129]
	v_mfma_f32_16x16x32_bf16 v[114:117], v[150:153], v[196:199], v[114:117]
	v_mfma_f32_16x16x32_bf16 v[98:101], v[150:153], v[204:207], v[98:101]
	v_mfma_f32_16x16x32_bf16 v[82:85], v[150:153], v[212:215], v[82:85]
	v_mfma_f32_16x16x32_bf16 v[122:125], v[158:161], v[182:185], v[122:125]
	v_mfma_f32_16x16x32_bf16 v[106:109], v[158:161], v[196:199], v[106:109]
	v_mfma_f32_16x16x32_bf16 v[90:93], v[158:161], v[204:207], v[90:93]
	v_mfma_f32_16x16x32_bf16 v[74:77], v[158:161], v[212:215], v[74:77]


	v_mfma_f32_16x16x32_bf16 v[118:121], v[162:165], v[178:181], v[118:121]
	v_mfma_f32_16x16x32_bf16 v[102:105], v[162:165], v[192:195], v[102:105]
	v_mfma_f32_16x16x32_bf16 v[86:89], v[162:165], v[200:203], v[86:89]
	v_mfma_f32_16x16x32_bf16 v[70:73], v[162:165], v[208:211], v[70:73]
	v_mfma_f32_16x16x32_bf16 v[110:113], v[170:173], v[178:181], v[110:113]
	v_mfma_f32_16x16x32_bf16 v[94:97], v[170:173], v[192:195], v[94:97]
	v_mfma_f32_16x16x32_bf16 v[78:81], v[170:173], v[200:203], v[78:81]
	v_mfma_f32_16x16x32_bf16 v[66:69], v[170:173], v[208:211], v[66:69]
	v_mfma_f32_16x16x32_bf16 v[118:121], v[166:169], v[182:185], v[118:121]
	v_mfma_f32_16x16x32_bf16 v[102:105], v[166:169], v[196:199], v[102:105]
	v_mfma_f32_16x16x32_bf16 v[86:89], v[166:169], v[204:207], v[86:89]
	v_mfma_f32_16x16x32_bf16 v[70:73], v[166:169], v[212:215], v[70:73]
	v_mfma_f32_16x16x32_bf16 v[110:113], v[174:177], v[182:185], v[110:113]
	v_mfma_f32_16x16x32_bf16 v[94:97], v[174:177], v[196:199], v[94:97]
	v_mfma_f32_16x16x32_bf16 v[78:81], v[174:177], v[204:207], v[78:81]
	v_mfma_f32_16x16x32_bf16 v[66:69], v[174:177], v[212:215], v[66:69]
	s_barrier
	s_setprio 0
	s_add_i32 s0, s0, s39
	v_lshl_add_u64 v[140:141], v[140:141], 0, s[84:85]
	s_mov_b32 m0, s0
	ds_read_b128 v[178:181], v145 offset:49152
	ds_read_b128 v[182:185], v145 offset:50176
	ds_read_b128 v[192:195], v145 offset:51200
	ds_read_b128 v[196:199], v145 offset:52224
	ds_read_b128 v[200:203], v145 offset:53248
	ds_read_b128 v[204:207], v145 offset:54272
	ds_read_b128 v[208:211], v145 offset:55296
	ds_read_b128 v[212:215], v145 offset:56320
	global_load_lds_dwordx4 v[140:141], off
	s_add_i32 m0, s0, 0x2000
	s_add_u32 s28, s28, 0x80080
	v_lshl_add_u64 v[140:141], v[188:189], 0, s[84:85]
	s_addc_u32 s29, s29, 0
	s_add_i32 s0, s1, s39
	global_load_lds_dwordx4 v[140:141], off
	v_lshl_add_u64 v[140:141], s[28:29], 0, v[186:187]
	s_mov_b32 m0, s0
	s_nop 0
	global_load_lds_dwordx4 v[140:141], off
	v_lshl_add_u64 v[140:141], s[28:29], 0, v[130:131]
	s_add_i32 m0, s0, 0x2000
	s_nop 0
	global_load_lds_dwordx4 v[140:141], off
	v_lshl_add_u64 v[140:141], v[216:217], 0, s[84:85]
	s_mov_b32 m0, s43
	s_nop 0
	global_load_lds_dwordx4 v[140:141], off
	v_lshl_add_u64 v[140:141], v[218:219], 0, s[84:85]
	s_mov_b32 m0, s44
	s_nop 0
	global_load_lds_dwordx4 v[140:141], off
	s_waitcnt vmcnt(8)
	s_waitcnt lgkmcnt(0)
	s_setprio 1
	s_barrier

	v_mfma_f32_16x16x32_bf16 v[62:65], v[146:149], v[178:181], v[62:65]
	v_mfma_f32_16x16x32_bf16 v[50:53], v[146:149], v[192:195], v[50:53]
	v_mfma_f32_16x16x32_bf16 v[34:37], v[146:149], v[200:203], v[34:37]
	v_mfma_f32_16x16x32_bf16 v[18:21], v[146:149], v[208:211], v[18:21]
	v_mfma_f32_16x16x32_bf16 v[58:61], v[154:157], v[178:181], v[58:61]
	v_mfma_f32_16x16x32_bf16 v[42:45], v[154:157], v[192:195], v[42:45]
	v_mfma_f32_16x16x32_bf16 v[26:29], v[154:157], v[200:203], v[26:29]
	v_mfma_f32_16x16x32_bf16 v[10:13], v[154:157], v[208:211], v[10:13]
	v_mfma_f32_16x16x32_bf16 v[62:65], v[150:153], v[182:185], v[62:65]
	v_mfma_f32_16x16x32_bf16 v[50:53], v[150:153], v[196:199], v[50:53]
	v_mfma_f32_16x16x32_bf16 v[34:37], v[150:153], v[204:207], v[34:37]
	v_mfma_f32_16x16x32_bf16 v[18:21], v[150:153], v[212:215], v[18:21]
	v_mfma_f32_16x16x32_bf16 v[58:61], v[158:161], v[182:185], v[58:61]
	v_mfma_f32_16x16x32_bf16 v[42:45], v[158:161], v[196:199], v[42:45]
	v_mfma_f32_16x16x32_bf16 v[26:29], v[158:161], v[204:207], v[26:29]
	v_mfma_f32_16x16x32_bf16 v[10:13], v[158:161], v[212:215], v[10:13]


	v_mfma_f32_16x16x32_bf16 v[54:57], v[162:165], v[178:181], v[54:57]
	v_mfma_f32_16x16x32_bf16 v[38:41], v[162:165], v[192:195], v[38:41]
	v_mfma_f32_16x16x32_bf16 v[22:25], v[162:165], v[200:203], v[22:25]
	v_mfma_f32_16x16x32_bf16 v[6:9], v[162:165], v[208:211], v[6:9]
	v_mfma_f32_16x16x32_bf16 v[46:49], v[170:173], v[178:181], v[46:49]
	v_mfma_f32_16x16x32_bf16 v[30:33], v[170:173], v[192:195], v[30:33]
	v_mfma_f32_16x16x32_bf16 v[14:17], v[170:173], v[200:203], v[14:17]
	v_mfma_f32_16x16x32_bf16 v[2:5], v[170:173], v[208:211], v[2:5]
	v_mfma_f32_16x16x32_bf16 v[54:57], v[166:169], v[182:185], v[54:57]
	v_mfma_f32_16x16x32_bf16 v[38:41], v[166:169], v[196:199], v[38:41]
	v_mfma_f32_16x16x32_bf16 v[22:25], v[166:169], v[204:207], v[22:25]
	v_mfma_f32_16x16x32_bf16 v[6:9], v[166:169], v[212:215], v[6:9]
	v_mfma_f32_16x16x32_bf16 v[46:49], v[174:177], v[182:185], v[46:49]
	v_mfma_f32_16x16x32_bf16 v[30:33], v[174:177], v[196:199], v[30:33]
	v_mfma_f32_16x16x32_bf16 v[14:17], v[174:177], v[204:207], v[14:17]
	v_mfma_f32_16x16x32_bf16 v[2:5], v[174:177], v[212:215], v[2:5]
	s_barrier
	s_setprio 0
	s_add_i32 s55, s55, 2
	s_add_u32 s26, s26, 0x100
	s_addc_u32 s27, s27, 0
	s_add_u32 s53, s53, 0x100
	s_addc_u32 s54, s54, 0
	s_cmp_gt_u32 s55, 29
	s_cbranch_scc0 .LBB0_443
	s_and_b64 vcc, exec, s[14:15]
	s_cbranch_vccz .LBB0_446
	s_barrier

.LBB0_1126:
	s_add_u32 s0, s28, 0xfff80080
	s_addc_u32 s1, s29, -1
	s_add_i32 s54, 0, 0x10000
	s_cmp_eq_u32 s53, 28
	s_cselect_b32 s35, s19, s1
	s_cselect_b32 s34, s25, s0
	s_cselect_b32 s31, s17, s52
	s_cselect_b32 s30, s27, s51
	s_add_i32 s55, 0, 0x14000
	v_add_u32_e32 v126, s54, v237
	v_add_u32_e32 v158, s55, v237
	ds_read_b128 v[90:93], v126
	ds_read_b128 v[102:105], v126 offset:1024
	ds_read_b128 v[114:117], v126 offset:2048
	ds_read_b128 v[126:129], v126 offset:3072
	ds_read_b128 v[138:141], v158
	ds_read_b128 v[142:145], v158 offset:1024
	ds_read_b128 v[154:157], v158 offset:2048
	ds_read_b128 v[158:161], v158 offset:3072
	v_lshl_add_u64 v[188:189], s[28:29], 0, v[198:199]
	s_add_i32 m0, s40, 0xc000
	ds_read_b128 v[162:165], v238
	ds_read_b128 v[166:169], v238 offset:1024
	ds_read_b128 v[170:173], v238 offset:2048
	ds_read_b128 v[174:177], v238 offset:3072
	ds_read_b128 v[178:181], v238 offset:4096
	ds_read_b128 v[182:185], v238 offset:5120
	ds_read_b128 v[202:205], v238 offset:6144
	ds_read_b128 v[206:209], v238 offset:7168
	global_load_lds_dwordx4 v[188:189], off
	v_lshl_add_u64 v[188:189], s[28:29], 0, v[200:201]
	s_add_i32 m0, s40, 0xe000
	s_nop 0
	global_load_lds_dwordx4 v[188:189], off
	s_waitcnt vmcnt(8)
	s_waitcnt lgkmcnt(0)
	s_setprio 1
	s_barrier

	v_mfma_f32_16x16x32_bf16 v[150:153], v[90:93], v[162:165], v[150:153]
	v_mfma_f32_16x16x32_bf16 v[122:125], v[90:93], v[170:173], v[122:125]
	v_mfma_f32_16x16x32_bf16 v[98:101], v[90:93], v[178:181], v[98:101]
	v_mfma_f32_16x16x32_bf16 v[78:81], v[90:93], v[202:205], v[78:81]
	v_mfma_f32_16x16x32_bf16 v[146:149], v[114:117], v[162:165], v[146:149]
	v_mfma_f32_16x16x32_bf16 v[118:121], v[114:117], v[170:173], v[118:121]
	v_mfma_f32_16x16x32_bf16 v[94:97], v[114:117], v[178:181], v[94:97]
	v_mfma_f32_16x16x32_bf16 v[74:77], v[114:117], v[202:205], v[74:77]
	v_mfma_f32_16x16x32_bf16 v[150:153], v[102:105], v[166:169], v[150:153]
	v_mfma_f32_16x16x32_bf16 v[122:125], v[102:105], v[174:177], v[122:125]
	v_mfma_f32_16x16x32_bf16 v[98:101], v[102:105], v[182:185], v[98:101]
	v_mfma_f32_16x16x32_bf16 v[78:81], v[102:105], v[206:209], v[78:81]
	v_mfma_f32_16x16x32_bf16 v[146:149], v[126:129], v[166:169], v[146:149]
	v_mfma_f32_16x16x32_bf16 v[118:121], v[126:129], v[174:177], v[118:121]
	v_mfma_f32_16x16x32_bf16 v[94:97], v[126:129], v[182:185], v[94:97]
	v_mfma_f32_16x16x32_bf16 v[74:77], v[126:129], v[206:209], v[74:77]


	v_mfma_f32_16x16x32_bf16 v[134:137], v[138:141], v[162:165], v[134:137]
	v_mfma_f32_16x16x32_bf16 v[110:113], v[138:141], v[170:173], v[110:113]
	v_mfma_f32_16x16x32_bf16 v[86:89], v[138:141], v[178:181], v[86:89]
	v_mfma_f32_16x16x32_bf16 v[70:73], v[138:141], v[202:205], v[70:73]
	v_mfma_f32_16x16x32_bf16 v[130:133], v[154:157], v[162:165], v[130:133]
	v_mfma_f32_16x16x32_bf16 v[106:109], v[154:157], v[170:173], v[106:109]
	v_mfma_f32_16x16x32_bf16 v[82:85], v[154:157], v[178:181], v[82:85]
	v_mfma_f32_16x16x32_bf16 v[66:69], v[154:157], v[202:205], v[66:69]
	v_mfma_f32_16x16x32_bf16 v[134:137], v[142:145], v[166:169], v[134:137]
	v_mfma_f32_16x16x32_bf16 v[110:113], v[142:145], v[174:177], v[110:113]
	v_mfma_f32_16x16x32_bf16 v[86:89], v[142:145], v[182:185], v[86:89]
	v_mfma_f32_16x16x32_bf16 v[70:73], v[142:145], v[206:209], v[70:73]
	v_mfma_f32_16x16x32_bf16 v[130:133], v[158:161], v[166:169], v[130:133]
	v_mfma_f32_16x16x32_bf16 v[106:109], v[158:161], v[174:177], v[106:109]
	v_mfma_f32_16x16x32_bf16 v[82:85], v[158:161], v[182:185], v[82:85]
	v_mfma_f32_16x16x32_bf16 v[66:69], v[158:161], v[206:209], v[66:69]
	s_barrier
	s_setprio 0
	s_add_i32 s0, s54, s39
	v_lshl_add_u64 v[188:189], s[30:31], 0, v[186:187]
	s_mov_b32 m0, s0
	ds_read_b128 v[162:165], v238 offset:16384
	ds_read_b128 v[166:169], v238 offset:17408
	ds_read_b128 v[170:173], v238 offset:18432
	ds_read_b128 v[174:177], v238 offset:19456
	ds_read_b128 v[178:181], v238 offset:20480
	ds_read_b128 v[182:185], v238 offset:21504
	ds_read_b128 v[202:205], v238 offset:22528
	ds_read_b128 v[206:209], v238 offset:23552
	global_load_lds_dwordx4 v[188:189], off
	s_add_i32 m0, s0, 0x2000
	s_add_u32 s0, s30, 0x80000
	v_lshl_add_u64 v[210:211], s[30:31], 0, v[196:197]
	s_addc_u32 s1, s31, 0
	s_add_i32 s54, s55, s39
	global_load_lds_dwordx4 v[210:211], off
	v_lshl_add_u64 v[212:213], s[0:1], 0, v[186:187]
	s_mov_b32 m0, s54
	v_lshl_add_u64 v[214:215], s[34:35], 0, v[194:195]
	global_load_lds_dwordx4 v[212:213], off
	v_lshl_add_u64 v[212:213], s[0:1], 0, v[196:197]
	s_add_i32 m0, s54, 0x2000
	s_nop 0
	global_load_lds_dwordx4 v[212:213], off
	v_lshl_add_u64 v[212:213], s[34:35], 0, v[192:193]
	s_mov_b32 m0, s40
	s_nop 0
	global_load_lds_dwordx4 v[212:213], off
	s_mov_b32 m0, s41
	s_nop 0
	global_load_lds_dwordx4 v[214:215], off
	s_waitcnt vmcnt(8)
	s_waitcnt lgkmcnt(0)
	s_setprio 1
	s_barrier

	v_mfma_f32_16x16x32_bf16 v[62:65], v[90:93], v[162:165], v[62:65]
	v_mfma_f32_16x16x32_bf16 v[46:49], v[90:93], v[170:173], v[46:49]
	v_mfma_f32_16x16x32_bf16 v[30:33], v[90:93], v[178:181], v[30:33]
	v_mfma_f32_16x16x32_bf16 v[14:17], v[90:93], v[202:205], v[14:17]
	v_mfma_f32_16x16x32_bf16 v[58:61], v[114:117], v[162:165], v[58:61]
	v_mfma_f32_16x16x32_bf16 v[42:45], v[114:117], v[170:173], v[42:45]
	v_mfma_f32_16x16x32_bf16 v[26:29], v[114:117], v[178:181], v[26:29]
	v_mfma_f32_16x16x32_bf16 v[10:13], v[114:117], v[202:205], v[10:13]
	v_mfma_f32_16x16x32_bf16 v[62:65], v[102:105], v[166:169], v[62:65]
	v_mfma_f32_16x16x32_bf16 v[46:49], v[102:105], v[174:177], v[46:49]
	v_mfma_f32_16x16x32_bf16 v[30:33], v[102:105], v[182:185], v[30:33]
	v_mfma_f32_16x16x32_bf16 v[14:17], v[102:105], v[206:209], v[14:17]
	v_mfma_f32_16x16x32_bf16 v[58:61], v[126:129], v[166:169], v[58:61]
	v_mfma_f32_16x16x32_bf16 v[42:45], v[126:129], v[174:177], v[42:45]
	v_mfma_f32_16x16x32_bf16 v[26:29], v[126:129], v[182:185], v[26:29]
	v_mfma_f32_16x16x32_bf16 v[10:13], v[126:129], v[206:209], v[10:13]


	v_mfma_f32_16x16x32_bf16 v[54:57], v[138:141], v[162:165], v[54:57]
	v_mfma_f32_16x16x32_bf16 v[38:41], v[138:141], v[170:173], v[38:41]
	v_mfma_f32_16x16x32_bf16 v[22:25], v[138:141], v[178:181], v[22:25]
	v_mfma_f32_16x16x32_bf16 v[6:9], v[138:141], v[202:205], v[6:9]
	v_mfma_f32_16x16x32_bf16 v[50:53], v[154:157], v[162:165], v[50:53]
	v_mfma_f32_16x16x32_bf16 v[34:37], v[154:157], v[170:173], v[34:37]
	v_mfma_f32_16x16x32_bf16 v[18:21], v[154:157], v[178:181], v[18:21]
	v_mfma_f32_16x16x32_bf16 v[2:5], v[154:157], v[202:205], v[2:5]
	v_mfma_f32_16x16x32_bf16 v[54:57], v[142:145], v[166:169], v[54:57]
	v_mfma_f32_16x16x32_bf16 v[38:41], v[142:145], v[174:177], v[38:41]
	v_mfma_f32_16x16x32_bf16 v[22:25], v[142:145], v[182:185], v[22:25]
	v_mfma_f32_16x16x32_bf16 v[6:9], v[142:145], v[206:209], v[6:9]
	v_mfma_f32_16x16x32_bf16 v[50:53], v[158:161], v[166:169], v[50:53]
	v_mfma_f32_16x16x32_bf16 v[34:37], v[158:161], v[174:177], v[34:37]
	v_mfma_f32_16x16x32_bf16 v[18:21], v[158:161], v[182:185], v[18:21]
	v_mfma_f32_16x16x32_bf16 v[2:5], v[158:161], v[206:209], v[2:5]
	s_barrier
	s_setprio 0
	s_add_i32 s54, 0, 0x18000
	s_add_i32 s55, 0, 0x1c000
	v_add_u32_e32 v126, s54, v237
	v_add_u32_e32 v158, s55, v237
	ds_read_b128 v[90:93], v126
	ds_read_b128 v[102:105], v126 offset:1024
	ds_read_b128 v[114:117], v126 offset:2048
	ds_read_b128 v[126:129], v126 offset:3072
	ds_read_b128 v[138:141], v158
	ds_read_b128 v[142:145], v158 offset:1024
	ds_read_b128 v[154:157], v158 offset:2048
	ds_read_b128 v[158:161], v158 offset:3072
	s_add_u32 s0, s34, 0x80000
	s_addc_u32 s1, s35, 0
	s_mov_b32 m0, s42
	v_lshl_add_u64 v[216:217], s[0:1], 0, v[192:193]
	ds_read_b128 v[162:165], v238 offset:32768
	ds_read_b128 v[166:169], v238 offset:33792
	ds_read_b128 v[170:173], v238 offset:34816
	ds_read_b128 v[174:177], v238 offset:35840
	ds_read_b128 v[178:181], v238 offset:36864
	ds_read_b128 v[182:185], v238 offset:37888
	ds_read_b128 v[202:205], v238 offset:38912
	ds_read_b128 v[206:209], v238 offset:39936
	global_load_lds_dwordx4 v[216:217], off
	v_lshl_add_u64 v[216:217], s[0:1], 0, v[194:195]
	s_mov_b32 m0, s43
	s_nop 0
	global_load_lds_dwordx4 v[216:217], off
	s_waitcnt vmcnt(8)
	s_waitcnt lgkmcnt(0)
	s_setprio 1
	s_barrier

	v_mfma_f32_16x16x32_bf16 v[150:153], v[90:93], v[162:165], v[150:153]
	v_mfma_f32_16x16x32_bf16 v[122:125], v[90:93], v[170:173], v[122:125]
	v_mfma_f32_16x16x32_bf16 v[98:101], v[90:93], v[178:181], v[98:101]
	v_mfma_f32_16x16x32_bf16 v[78:81], v[90:93], v[202:205], v[78:81]
	v_mfma_f32_16x16x32_bf16 v[146:149], v[114:117], v[162:165], v[146:149]
	v_mfma_f32_16x16x32_bf16 v[118:121], v[114:117], v[170:173], v[118:121]
	v_mfma_f32_16x16x32_bf16 v[94:97], v[114:117], v[178:181], v[94:97]
	v_mfma_f32_16x16x32_bf16 v[74:77], v[114:117], v[202:205], v[74:77]
	v_mfma_f32_16x16x32_bf16 v[150:153], v[102:105], v[166:169], v[150:153]
	v_mfma_f32_16x16x32_bf16 v[122:125], v[102:105], v[174:177], v[122:125]
	v_mfma_f32_16x16x32_bf16 v[98:101], v[102:105], v[182:185], v[98:101]
	v_mfma_f32_16x16x32_bf16 v[78:81], v[102:105], v[206:209], v[78:81]
	v_mfma_f32_16x16x32_bf16 v[146:149], v[126:129], v[166:169], v[146:149]
	v_mfma_f32_16x16x32_bf16 v[118:121], v[126:129], v[174:177], v[118:121]
	v_mfma_f32_16x16x32_bf16 v[94:97], v[126:129], v[182:185], v[94:97]
	v_mfma_f32_16x16x32_bf16 v[74:77], v[126:129], v[206:209], v[74:77]


	v_mfma_f32_16x16x32_bf16 v[134:137], v[138:141], v[162:165], v[134:137]
	v_mfma_f32_16x16x32_bf16 v[110:113], v[138:141], v[170:173], v[110:113]
	v_mfma_f32_16x16x32_bf16 v[86:89], v[138:141], v[178:181], v[86:89]
	v_mfma_f32_16x16x32_bf16 v[70:73], v[138:141], v[202:205], v[70:73]
	v_mfma_f32_16x16x32_bf16 v[130:133], v[154:157], v[162:165], v[130:133]
	v_mfma_f32_16x16x32_bf16 v[106:109], v[154:157], v[170:173], v[106:109]
	v_mfma_f32_16x16x32_bf16 v[82:85], v[154:157], v[178:181], v[82:85]
	v_mfma_f32_16x16x32_bf16 v[66:69], v[154:157], v[202:205], v[66:69]
	v_mfma_f32_16x16x32_bf16 v[134:137], v[142:145], v[166:169], v[134:137]
	v_mfma_f32_16x16x32_bf16 v[110:113], v[142:145], v[174:177], v[110:113]
	v_mfma_f32_16x16x32_bf16 v[86:89], v[142:145], v[182:185], v[86:89]
	v_mfma_f32_16x16x32_bf16 v[70:73], v[142:145], v[206:209], v[70:73]
	v_mfma_f32_16x16x32_bf16 v[130:133], v[158:161], v[166:169], v[130:133]
	v_mfma_f32_16x16x32_bf16 v[106:109], v[158:161], v[174:177], v[106:109]
	v_mfma_f32_16x16x32_bf16 v[82:85], v[158:161], v[182:185], v[82:85]
	v_mfma_f32_16x16x32_bf16 v[66:69], v[158:161], v[206:209], v[66:69]
	s_barrier
	s_setprio 0
	s_add_i32 s0, s54, s39
	v_lshl_add_u64 v[188:189], v[188:189], 0, s[84:85]
	s_mov_b32 m0, s0
	ds_read_b128 v[162:165], v238 offset:49152
	ds_read_b128 v[166:169], v238 offset:50176
	ds_read_b128 v[170:173], v238 offset:51200
	ds_read_b128 v[174:177], v238 offset:52224
	ds_read_b128 v[178:181], v238 offset:53248
	ds_read_b128 v[182:185], v238 offset:54272
	ds_read_b128 v[202:205], v238 offset:55296
	ds_read_b128 v[206:209], v238 offset:56320
	global_load_lds_dwordx4 v[188:189], off
	s_add_i32 m0, s0, 0x2000
	s_add_u32 s0, s30, 0x80080
	v_lshl_add_u64 v[188:189], v[210:211], 0, s[84:85]
	s_addc_u32 s1, s31, 0
	s_add_i32 s30, s55, s39
	global_load_lds_dwordx4 v[188:189], off
	v_lshl_add_u64 v[188:189], s[0:1], 0, v[186:187]
	s_mov_b32 m0, s30
	s_nop 0
	global_load_lds_dwordx4 v[188:189], off
	v_lshl_add_u64 v[188:189], s[0:1], 0, v[196:197]
	s_add_i32 m0, s30, 0x2000
	s_nop 0
	global_load_lds_dwordx4 v[188:189], off
	v_lshl_add_u64 v[188:189], v[212:213], 0, s[84:85]
	s_mov_b32 m0, s47
	s_nop 0
	global_load_lds_dwordx4 v[188:189], off
	v_lshl_add_u64 v[188:189], v[214:215], 0, s[84:85]
	s_mov_b32 m0, s48
	s_nop 0
	global_load_lds_dwordx4 v[188:189], off
	s_waitcnt vmcnt(8)
	s_waitcnt lgkmcnt(0)
	s_setprio 1
	s_barrier

	v_mfma_f32_16x16x32_bf16 v[62:65], v[90:93], v[162:165], v[62:65]
	v_mfma_f32_16x16x32_bf16 v[46:49], v[90:93], v[170:173], v[46:49]
	v_mfma_f32_16x16x32_bf16 v[30:33], v[90:93], v[178:181], v[30:33]
	v_mfma_f32_16x16x32_bf16 v[14:17], v[90:93], v[202:205], v[14:17]
	v_mfma_f32_16x16x32_bf16 v[58:61], v[114:117], v[162:165], v[58:61]
	v_mfma_f32_16x16x32_bf16 v[42:45], v[114:117], v[170:173], v[42:45]
	v_mfma_f32_16x16x32_bf16 v[26:29], v[114:117], v[178:181], v[26:29]
	v_mfma_f32_16x16x32_bf16 v[10:13], v[114:117], v[202:205], v[10:13]
	v_mfma_f32_16x16x32_bf16 v[62:65], v[102:105], v[166:169], v[62:65]
	v_mfma_f32_16x16x32_bf16 v[46:49], v[102:105], v[174:177], v[46:49]
	v_mfma_f32_16x16x32_bf16 v[30:33], v[102:105], v[182:185], v[30:33]
	v_mfma_f32_16x16x32_bf16 v[14:17], v[102:105], v[206:209], v[14:17]
	v_mfma_f32_16x16x32_bf16 v[58:61], v[126:129], v[166:169], v[58:61]
	v_mfma_f32_16x16x32_bf16 v[42:45], v[126:129], v[174:177], v[42:45]
	v_mfma_f32_16x16x32_bf16 v[26:29], v[126:129], v[182:185], v[26:29]
	v_mfma_f32_16x16x32_bf16 v[10:13], v[126:129], v[206:209], v[10:13]


	v_mfma_f32_16x16x32_bf16 v[54:57], v[138:141], v[162:165], v[54:57]
	v_mfma_f32_16x16x32_bf16 v[38:41], v[138:141], v[170:173], v[38:41]
	v_mfma_f32_16x16x32_bf16 v[22:25], v[138:141], v[178:181], v[22:25]
	v_mfma_f32_16x16x32_bf16 v[6:9], v[138:141], v[202:205], v[6:9]
	v_mfma_f32_16x16x32_bf16 v[50:53], v[154:157], v[162:165], v[50:53]
	v_mfma_f32_16x16x32_bf16 v[34:37], v[154:157], v[170:173], v[34:37]
	v_mfma_f32_16x16x32_bf16 v[18:21], v[154:157], v[178:181], v[18:21]
	v_mfma_f32_16x16x32_bf16 v[2:5], v[154:157], v[202:205], v[2:5]
	v_mfma_f32_16x16x32_bf16 v[54:57], v[142:145], v[166:169], v[54:57]
	v_mfma_f32_16x16x32_bf16 v[38:41], v[142:145], v[174:177], v[38:41]
	v_mfma_f32_16x16x32_bf16 v[22:25], v[142:145], v[182:185], v[22:25]
	v_mfma_f32_16x16x32_bf16 v[6:9], v[142:145], v[206:209], v[6:9]
	v_mfma_f32_16x16x32_bf16 v[50:53], v[158:161], v[166:169], v[50:53]
	v_mfma_f32_16x16x32_bf16 v[34:37], v[158:161], v[174:177], v[34:37]
	v_mfma_f32_16x16x32_bf16 v[18:21], v[158:161], v[182:185], v[18:21]
	v_mfma_f32_16x16x32_bf16 v[2:5], v[158:161], v[206:209], v[2:5]
	s_barrier
	s_setprio 0
	s_add_i32 s53, s53, 2
	s_add_u32 s28, s28, 0x100
	s_addc_u32 s29, s29, 0
	s_add_u32 s51, s51, 0x100
	s_addc_u32 s52, s52, 0
	s_cmp_gt_u32 s53, 29
	s_cbranch_scc0 .LBB0_1126
	s_and_b64 vcc, exec, s[14:15]
	s_cbranch_vccz .LBB0_1129
	s_barrier
